# scan ring deepened to 4 LDS slots (loads run 3 steps ahead) using the idle sibling half's LDS
# speedup vs baseline: 1.0005x; 1.0005x over previous
; DI int otid() { int t = threadIdx.x & 255; asm volatile("" : "+v"(t)); return t; }
; DI void dn_c2_unit(const Params& p, int dh, int w) {
;   unsigned char* ws = p.ws;
;   const int tid = otid(), lane = tid & 63;
;   if (tid >= 64) return;
;   const h16* cw = (const h16*)(ws + OFF_CW) + (size_t)dh * 256 * 4096;
;   const h16* ckd = (const h16*)(ws + OFF_CKD) + (size_t)dh * 256 * 4096;
;   const float* cu = (const float*)(ws + OFF_CU) + (size_t)dh * 256 * 4096;
;   const float* cdl = (const float*)(ws + OFF_CDL) + (size_t)dh * 256;
;   h16* cs = (h16*)(ws + OFF_CS) + (size_t)dh * 256 * 4096;
;   h16* cvn = (h16*)(ws + OFF_CVN) + (size_t)dh * 256 * 4096;
;   f4v S[4];
; #pragma unroll
;   for (int i = 0; i < 4; ++i) S[i] = (f4v){0.f, 0.f, 0.f, 0.f};
;   h8v wA[4][2], kA[4][2]; f4v uu[4]; float dl;
; #pragma unroll
;   for (int t = 0; t < 4; ++t) {
; #pragma unroll
;     for (int s = 0; s < 2; ++s) {
;       wA[t][s] = *(const h8v*)&cw[((t * 2 + s) * 64 + lane) * 8];
;       kA[t][s] = *(const h8v*)&ckd[((t * 2 + s) * 64 + lane) * 8];
;     }
;     uu[t] = *(const f4v*)&cu[((w * 4 + t) * 64 + lane) * 4];
;   }
;   dl = cdl[0];
.LBB0_953:
	s_andn2_saveexec_b64 s[2:3], s[86:87]
	s_cbranch_execz .LBB0_959
	v_mov_b32_e32 v2, v182
	s_nop 0
	v_cmp_gt_i32_e32 vcc, 64, v2
	s_and_saveexec_b64 s[4:5], vcc
	s_cbranch_execz .LBB0_958
	v_ashrrev_i32_e32 v78, 2, v1
	v_ashrrev_i32_e32 v79, 31, v78
	v_readlane_b32 s6, v254, 23
	v_lshlrev_b64 v[150:151], 22, v[78:79]
	v_readlane_b32 s7, v254, 24
	v_and_b32_e32 v86, 63, v2
	v_lshlrev_b64 v[152:153], 21, v[78:79]
	v_lshl_add_u64 v[2:3], s[6:7], 0, v[150:151]
	v_readlane_b32 s6, v254, 21
	v_readlane_b32 s7, v254, 22
	v_lshlrev_b32_e32 v82, 4, v86
	v_mov_b32_e32 v83, v0
	v_lshl_add_u64 v[10:11], s[6:7], 0, v[152:153]
	v_readlane_b32 s6, v254, 25
	v_readlane_b32 s7, v254, 26
	v_lshlrev_b32_e32 v8, 10, v1
	v_lshl_add_u64 v[4:5], v[10:11], 0, v[82:83]
	v_lshl_add_u64 v[12:13], s[6:7], 0, v[152:153]
	v_lshl_add_u64 v[6:7], v[12:13], 0, v[82:83]
	v_and_b32_e32 v171, 0xc00, v8
	v_lshlrev_b32_e32 v83, 2, v86
	v_or_b32_e32 v8, v83, v171
	v_lshlrev_b32_e32 v8, 2, v8
	v_mov_b32_e32 v9, v0
	global_load_dwordx4 v[50:53], v[4:5], off
	global_load_dwordx4 v[18:21], v[4:5], off offset:1024
	global_load_dwordx4 v[70:73], v[6:7], off
	global_load_dwordx4 v[14:17], v[6:7], off offset:1024
	v_lshl_add_u64 v[84:85], v[2:3], 0, v[8:9]
	s_mov_b64 s[38:39], 0x2000
	v_lshl_add_u64 v[234:235], v[4:5], 0, s[38:39]
	v_lshl_add_u64 v[238:239], v[6:7], 0, s[38:39]
	s_mov_b64 s[40:41], 0x3000
	v_lshl_add_u64 v[236:237], v[4:5], 0, s[40:41]
	v_lshl_add_u64 v[240:241], v[6:7], 0, s[40:41]
	s_mov_b64 s[40:41], 0x4000
	v_lshl_add_u64 v[242:243], v[84:85], 0, s[40:41]
	global_load_dwordx4 v[26:29], v[4:5], off offset:2048
	global_load_dwordx4 v[22:25], v[4:5], off offset:3072
	global_load_dwordx4 v[38:41], v[6:7], off offset:2048
	s_nop 0
	global_load_dwordx4 v[2:5], v[6:7], off offset:3072
	global_load_dwordx4 v[58:61], v[84:85], off
	global_load_dwordx4 v[54:57], v[84:85], off offset:1024
	v_or_b32_e32 v6, 0x1000, v82
	v_mov_b32_e32 v7, v0
	v_lshl_add_u64 v[8:9], v[10:11], 0, v[6:7]
	v_lshl_add_u64 v[6:7], v[12:13], 0, v[6:7]
	global_load_dwordx4 v[34:37], v[8:9], off
	global_load_dwordx4 v[30:33], v[6:7], off
	v_or_b32_e32 v6, 0x1400, v82
	v_mov_b32_e32 v7, v0
	v_or_b32_e32 v42, 0x1800, v82
	v_mov_b32_e32 v43, v0
	v_or_b32_e32 v66, 0x1c00, v82
	v_mov_b32_e32 v67, v0
	v_lshl_add_u64 v[8:9], v[10:11], 0, v[6:7]
	v_lshl_add_u64 v[6:7], v[12:13], 0, v[6:7]
	v_lshl_add_u64 v[44:45], v[10:11], 0, v[42:43]
	v_lshl_add_u64 v[42:43], v[12:13], 0, v[42:43]
	v_lshl_add_u64 v[10:11], v[10:11], 0, v[66:67]
	v_lshl_add_u64 v[12:13], v[12:13], 0, v[66:67]
	v_readlane_b32 s6, v254, 19
	v_lshlrev_b64 v[80:81], 10, v[78:79]
	global_load_dwordx4 v[46:49], v[8:9], off
	s_nop 0
	global_load_dwordx4 v[6:9], v[6:7], off
	s_nop 0
	global_load_dwordx4 v[62:65], v[44:45], off
	s_nop 0
	global_load_dwordx4 v[42:45], v[42:43], off
	s_nop 0
	global_load_dwordx4 v[66:69], v[10:11], off
	s_nop 0
	global_load_dwordx4 v[10:13], v[12:13], off
	s_nop 0
	global_load_dwordx4 v[74:77], v[84:85], off offset:2048
	global_load_dwordx4 v[90:93], v[84:85], off offset:3072
	v_readlane_b32 s7, v254, 20
	v_lshlrev_b32_e32 v174, 3, v86
	v_lshlrev_b64 v[154:155], 20, v[78:79]
	v_lshl_add_u64 v[84:85], s[6:7], 0, v[80:81]
	v_lshl_add_u64 v[244:245], v[84:85], 0, 4
	global_load_dword v160, v[84:85], off
	v_and_b32_e32 v84, 0xc00, v164
	v_or_b32_e32 v78, v84, v174
	v_lshl_or_b32 v158, v78, 1, v152
	v_or_b32_e32 v78, v84, v83
	v_readlane_b32 s16, v252, 3
	s_mov_b64 s[6:7], 0x1df08004
	v_lshl_or_b32 v150, v78, 2, v150
	v_mov_b32_e32 v78, 0
	v_readlane_b32 s17, v252, 4
	v_lshl_add_u64 v[156:157], v[80:81], 0, s[6:7]
	v_mov_b32_e32 v159, v153
	v_or_b32_e32 v152, v152, v82
	s_movk_i32 s6, 0xff
	v_mov_b32_e32 v79, v78
	v_mov_b32_e32 v80, v78
	v_mov_b32_e32 v81, v78
	v_mov_b32_e32 v94, v78
	v_mov_b32_e32 v95, v78
	v_mov_b32_e32 v96, v78
	v_mov_b32_e32 v97, v78
	v_mov_b32_e32 v86, v78
	v_mov_b32_e32 v87, v78
	v_mov_b32_e32 v88, v78
	v_mov_b32_e32 v89, v78
	v_mov_b32_e32 v82, v78
	v_mov_b32_e32 v83, v78
	v_mov_b32_e32 v84, v78
	v_mov_b32_e32 v85, v78
	v_readlane_b32 s20, v252, 7
	v_readlane_b32 s21, v252, 8
	s_mov_b64 s[16:17], 0x2000
	v_readlane_b32 s18, v252, 5
	v_readlane_b32 s19, v252, 6
	v_readlane_b32 s22, v252, 9
	v_readlane_b32 s23, v252, 10
	v_and_b32_e32 v247, 63, v182
	v_lshlrev_b32_e32 v247, 4, v247
	s_mov_b32 s37, 16
	s_add_u32 s36, s37, 0x15000
	s_add_u32 s34, s37, 0x5400
	s_waitcnt vmcnt(21)
; DI void dn_c2_unit(const Params& p, int dh, int w) {
;     ...
;   for (int n = 0; n < 256; ++n) {
;     h8v wN[4][2], kN[4][2]; f4v uN[4]; float dlN = 0.f;
;     const int nn = (n + 1 < 256) ? n + 1 : n;
;     {
;       const h16* cw1 = cw + (size_t)nn * 4096; const h16* ck1 = ckd + (size_t)nn * 4096; const float* cu1 = cu + (size_t)nn * 4096;
; #pragma unroll
;       for (int t = 0; t < 4; ++t) {
; #pragma unroll
;         for (int s = 0; s < 2; ++s) {
;           wN[t][s] = *(const h8v*)&cw1[((t * 2 + s) * 64 + lane) * 8];
;           kN[t][s] = *(const h8v*)&ck1[((t * 2 + s) * 64 + lane) * 8];
;         }
;         uN[t] = *(const f4v*)&cu1[((w * 4 + t) * 64 + lane) * 4];
;       }
;       dlN = cdl[nn];
;     }
	s_mov_b32 m0, s34
	s_nop 0
	global_load_lds_dwordx4 v[234:235], off
	global_load_lds_dwordx4 v[234:235], off offset:1024
	global_load_lds_dwordx4 v[234:235], off offset:2048
	global_load_lds_dwordx4 v[234:235], off offset:3072
	s_add_u32 m0, s34, 0x1000
	s_nop 0
	global_load_lds_dwordx4 v[236:237], off
	global_load_lds_dwordx4 v[236:237], off offset:1024
	global_load_lds_dwordx4 v[236:237], off offset:2048
	global_load_lds_dwordx4 v[236:237], off offset:3072
	s_add_u32 m0, s34, 0x2000
	s_nop 0
	global_load_lds_dwordx4 v[238:239], off
	global_load_lds_dwordx4 v[238:239], off offset:1024
	global_load_lds_dwordx4 v[238:239], off offset:2048
	global_load_lds_dwordx4 v[238:239], off offset:3072
	s_add_u32 m0, s34, 0x3000
	s_nop 0
	global_load_lds_dwordx4 v[240:241], off
	global_load_lds_dwordx4 v[240:241], off offset:1024
	global_load_lds_dwordx4 v[240:241], off offset:2048
	global_load_lds_dwordx4 v[240:241], off offset:3072
	s_add_u32 m0, s34, 0x4000
	s_nop 0
	global_load_lds_dwordx4 v[242:243], off
	global_load_lds_dwordx4 v[242:243], off offset:1024
	global_load_lds_dwordx4 v[242:243], off offset:2048
	global_load_lds_dwordx4 v[242:243], off offset:3072
	s_add_u32 m0, s34, 0x5000
	s_nop 0
	global_load_lds_dword v[244:245], off
	v_lshl_add_u64 v[234:235], v[234:235], 0, s[38:39]
	v_lshl_add_u64 v[236:237], v[236:237], 0, s[38:39]
	v_lshl_add_u64 v[238:239], v[238:239], 0, s[38:39]
	v_lshl_add_u64 v[240:241], v[240:241], 0, s[38:39]
	v_lshl_add_u64 v[242:243], v[242:243], 0, s[40:41]
	v_lshl_add_u64 v[244:245], v[244:245], 0, 4
	s_add_u32 s34, s34, 0x5400
	s_mov_b32 m0, s34
	s_nop 0
	global_load_lds_dwordx4 v[234:235], off
	global_load_lds_dwordx4 v[234:235], off offset:1024
	global_load_lds_dwordx4 v[234:235], off offset:2048
	global_load_lds_dwordx4 v[234:235], off offset:3072
	s_add_u32 m0, s34, 0x1000
	s_nop 0
	global_load_lds_dwordx4 v[236:237], off
	global_load_lds_dwordx4 v[236:237], off offset:1024
	global_load_lds_dwordx4 v[236:237], off offset:2048
	global_load_lds_dwordx4 v[236:237], off offset:3072
	s_add_u32 m0, s34, 0x2000
	s_nop 0
	global_load_lds_dwordx4 v[238:239], off
	global_load_lds_dwordx4 v[238:239], off offset:1024
	global_load_lds_dwordx4 v[238:239], off offset:2048
	global_load_lds_dwordx4 v[238:239], off offset:3072
	s_add_u32 m0, s34, 0x3000
	s_nop 0
	global_load_lds_dwordx4 v[240:241], off
	global_load_lds_dwordx4 v[240:241], off offset:1024
	global_load_lds_dwordx4 v[240:241], off offset:2048
	global_load_lds_dwordx4 v[240:241], off offset:3072
	s_add_u32 m0, s34, 0x4000
	s_nop 0
	global_load_lds_dwordx4 v[242:243], off
	global_load_lds_dwordx4 v[242:243], off offset:1024
	global_load_lds_dwordx4 v[242:243], off offset:2048
	global_load_lds_dwordx4 v[242:243], off offset:3072
	s_add_u32 m0, s34, 0x5000
	s_nop 0
	global_load_lds_dword v[244:245], off
	v_lshl_add_u64 v[234:235], v[234:235], 0, s[38:39]
	v_lshl_add_u64 v[236:237], v[236:237], 0, s[38:39]
	v_lshl_add_u64 v[238:239], v[238:239], 0, s[38:39]
	v_lshl_add_u64 v[240:241], v[240:241], 0, s[38:39]
	v_lshl_add_u64 v[242:243], v[242:243], 0, s[40:41]
	v_lshl_add_u64 v[244:245], v[244:245], 0, 4
	s_add_u32 s34, s34, 0x5400
	s_mov_b32 m0, s34
	s_nop 0
	global_load_lds_dwordx4 v[234:235], off
	global_load_lds_dwordx4 v[234:235], off offset:1024
	global_load_lds_dwordx4 v[234:235], off offset:2048
	global_load_lds_dwordx4 v[234:235], off offset:3072
	s_add_u32 m0, s34, 0x1000
	s_nop 0
	global_load_lds_dwordx4 v[236:237], off
	global_load_lds_dwordx4 v[236:237], off offset:1024
	global_load_lds_dwordx4 v[236:237], off offset:2048
	global_load_lds_dwordx4 v[236:237], off offset:3072
	s_add_u32 m0, s34, 0x2000
	s_nop 0
	global_load_lds_dwordx4 v[238:239], off
	global_load_lds_dwordx4 v[238:239], off offset:1024
	global_load_lds_dwordx4 v[238:239], off offset:2048
	global_load_lds_dwordx4 v[238:239], off offset:3072
	s_add_u32 m0, s34, 0x3000
	s_nop 0
	global_load_lds_dwordx4 v[240:241], off
	global_load_lds_dwordx4 v[240:241], off offset:1024
	global_load_lds_dwordx4 v[240:241], off offset:2048
	global_load_lds_dwordx4 v[240:241], off offset:3072
	s_add_u32 m0, s34, 0x4000
	s_nop 0
	global_load_lds_dwordx4 v[242:243], off
	global_load_lds_dwordx4 v[242:243], off offset:1024
	global_load_lds_dwordx4 v[242:243], off offset:2048
	global_load_lds_dwordx4 v[242:243], off offset:3072
	s_add_u32 m0, s34, 0x5000
	s_nop 0
	global_load_lds_dword v[244:245], off
	v_lshl_add_u64 v[234:235], v[234:235], 0, s[38:39]
	v_lshl_add_u64 v[236:237], v[236:237], 0, s[38:39]
	v_lshl_add_u64 v[238:239], v[238:239], 0, s[38:39]
	v_lshl_add_u64 v[240:241], v[240:241], 0, s[38:39]
	v_lshl_add_u64 v[242:243], v[242:243], 0, s[40:41]
	v_lshl_add_u64 v[244:245], v[244:245], 0, 4
	s_mov_b32 s34, s37
	s_add_u32 s35, s37, 0x5400
	s_waitcnt vmcnt(63)
.LBB0_956:
	s_cmp_gt_u32 s6, 252
	s_cbranch_scc1 .Lscan_early_wait
	s_waitcnt vmcnt(54)
	s_branch .Lscan_wait_done
.Lscan_early_wait:
	s_waitcnt vmcnt(42)
; DI f4v mfma16(h8v a, h8v b, f4v c) { return __builtin_amdgcn_mfma_f32_16x16x32_f16(a, b, c, 0, 0, 0); }
; DI void dn_c2_unit(const Params& p, int dh, int w) {
;     ...
;   for (int n = 0; n < 256; ++n) {
;     h8v wN[4][2], kN[4][2]; f4v uN[4]; float dlN = 0.f;
;     const int nn = (n + 1 < 256) ? n + 1 : n;
;     {
;       const h16* cw1 = cw + (size_t)nn * 4096; const h16* ck1 = ckd + (size_t)nn * 4096; const float* cu1 = cu + (size_t)nn * 4096;
; #pragma unroll
;       for (int t = 0; t < 4; ++t) {
; #pragma unroll
;         for (int s = 0; s < 2; ++s) {
;           wN[t][s] = *(const h8v*)&cw1[((t * 2 + s) * 64 + lane) * 8];
;           kN[t][s] = *(const h8v*)&ck1[((t * 2 + s) * 64 + lane) * 8];
;         }
;         uN[t] = *(const f4v*)&cu1[((w * 4 + t) * 64 + lane) * 4];
;       }
;       dlN = cdl[nn];
;     }
;     h8v Sb[2];
;     Sb[0] = pack8(S[0], S[1]); Sb[1] = pack8(S[2], S[3]);
;     h16* cs1 = cs + (size_t)n * 4096; h16* cv1 = cvn + (size_t)n * 4096;
;     *(h8v*)&cs1[((w * 2 + 0) * 64 + lane) * 8] = Sb[0];
;     *(h8v*)&cs1[((w * 2 + 1) * 64 + lane) * 8] = Sb[1];
;     f4v vn[4];
; #pragma unroll
;     for (int t = 0; t < 4; ++t) { vn[t] = uu[t]; vn[t] = mfma16(wA[t][0], Sb[0], vn[t]); vn[t] = mfma16(wA[t][1], Sb[1], vn[t]); }
;     h8v Vb[2];
;     Vb[0] = pack8(vn[0], vn[1]); Vb[1] = pack8(vn[2], vn[3]);
;     *(h8v*)&cv1[((w * 2 + 0) * 64 + lane) * 8] = Vb[0];
;     *(h8v*)&cv1[((w * 2 + 1) * 64 + lane) * 8] = Vb[1];
; #pragma unroll
;     for (int t = 0; t < 4; ++t) { S[t] *= dl; S[t] = mfma16(kA[t][0], Vb[0], S[t]); S[t] = mfma16(kA[t][1], Vb[1], S[t]); }
; #pragma unroll
;     for (int t = 0; t < 4; ++t) { wA[t][0] = wN[t][0]; wA[t][1] = wN[t][1]; kA[t][0] = kN[t][0]; kA[t][1] = kN[t][1]; uu[t] = uN[t]; }
;     dl = dlN;
;   }
.Lscan_wait_done:
	s_mov_b32 m0, s34
	s_nop 0
	global_load_lds_dwordx4 v[234:235], off
	global_load_lds_dwordx4 v[234:235], off offset:1024
	global_load_lds_dwordx4 v[234:235], off offset:2048
	global_load_lds_dwordx4 v[234:235], off offset:3072
	s_add_u32 m0, s34, 0x1000
	s_nop 0
	global_load_lds_dwordx4 v[236:237], off
	global_load_lds_dwordx4 v[236:237], off offset:1024
	global_load_lds_dwordx4 v[236:237], off offset:2048
	global_load_lds_dwordx4 v[236:237], off offset:3072
	s_add_u32 m0, s34, 0x2000
	s_nop 0
	global_load_lds_dwordx4 v[238:239], off
	global_load_lds_dwordx4 v[238:239], off offset:1024
	global_load_lds_dwordx4 v[238:239], off offset:2048
	global_load_lds_dwordx4 v[238:239], off offset:3072
	s_add_u32 m0, s34, 0x3000
	s_nop 0
	global_load_lds_dwordx4 v[240:241], off
	global_load_lds_dwordx4 v[240:241], off offset:1024
	global_load_lds_dwordx4 v[240:241], off offset:2048
	global_load_lds_dwordx4 v[240:241], off offset:3072
	s_add_u32 m0, s34, 0x4000
	s_nop 0
	global_load_lds_dwordx4 v[242:243], off
	global_load_lds_dwordx4 v[242:243], off offset:1024
	global_load_lds_dwordx4 v[242:243], off offset:2048
	global_load_lds_dwordx4 v[242:243], off offset:3072
	s_add_u32 m0, s34, 0x5000
	s_nop 0
	global_load_lds_dword v[244:245], off
	v_lshl_add_u64 v[234:235], v[234:235], 0, s[38:39]
	v_lshl_add_u64 v[236:237], v[236:237], 0, s[38:39]
	v_lshl_add_u64 v[238:239], v[238:239], 0, s[38:39]
	v_lshl_add_u64 v[240:241], v[240:241], 0, s[38:39]
	v_lshl_add_u64 v[242:243], v[242:243], 0, s[40:41]
	v_lshl_add_u64 v[244:245], v[244:245], 0, 4
	v_add_u32_e32 v246, s35, v247
	v_mov_b32_e32 v248, s35
	s_add_u32 s34, s34, 0x5400
	s_cmp_ge_u32 s34, s36
	s_cselect_b32 s34, s37, s34
	s_add_u32 s35, s35, 0x5400
	s_cmp_ge_u32 s35, s36
	s_cselect_b32 s35, s37, s35
	v_mov_b64_e32 v[178:179], v[20:21]
	v_mov_b64_e32 v[176:177], v[18:19]
	v_mov_b64_e32 v[148:149], v[24:25]
	v_mov_b64_e32 v[146:147], v[22:23]
	s_nop 0
	v_mov_b64_e32 v[132:133], v[28:29]
	v_mov_b64_e32 v[140:141], v[36:37]
	v_mov_b64_e32 v[130:131], v[26:27]
	v_mov_b64_e32 v[138:139], v[34:35]
	v_mov_b64_e32 v[218:219], v[64:65]
	v_mov_b64_e32 v[216:217], v[62:63]
	v_mov_b64_e32 v[120:121], v[60:61]
	v_mov_b64_e32 v[128:129], v[56:57]
	v_mov_b64_e32 v[118:119], v[58:59]
	v_mov_b64_e32 v[126:127], v[54:55]
	v_mov_b64_e32 v[144:145], v[48:49]
	v_cvt_pk_f16_f32 v101, v96, v97
	v_cvt_pk_f16_f32 v100, v94, v95
	v_cvt_pk_f16_f32 v99, v80, v81
	v_cvt_pk_f16_f32 v98, v78, v79
	v_mov_b64_e32 v[142:143], v[46:47]
	v_mov_b64_e32 v[136:137], v[68:69]
	ds_read_b128 v[18:21], v246 offset:1024
	ds_read_b128 v[26:29], v246 offset:2048
	ds_read_b128 v[106:109], v246 offset:9216
	s_nop 0
	ds_read_b128 v[22:25], v246 offset:3072
	s_nop 0
	ds_read_b128 v[110:113], v246 offset:10240
	ds_read_b128 v[114:117], v246 offset:11264
	ds_read_b128 v[58:61], v246 offset:16384
	ds_read_b128 v[54:57], v246 offset:17408
	v_mfma_f32_16x16x32_f16 v[220:223], v[50:53], v[98:101], v[118:121]
	ds_read_b128 v[34:37], v246 offset:4096
	s_nop 1
	ds_read_b128 v[118:121], v246 offset:8192
	ds_read_b128 v[122:125], v246 offset:12288
	v_mov_b64_e32 v[134:135], v[66:67]
	v_mfma_f32_16x16x32_f16 v[224:227], v[130:133], v[98:101], v[126:129]
	ds_read_b128 v[46:49], v246 offset:5120
	s_nop 1
	ds_read_b128 v[126:129], v246 offset:13312
	ds_read_b128 v[130:133], v246 offset:15360
	v_cvt_pk_f16_f32 v105, v84, v85
	v_cvt_pk_f16_f32 v104, v82, v83
	v_mfma_f32_16x16x32_f16 v[228:231], v[138:141], v[98:101], v[74:77]
	ds_read_b128 v[138:141], v246 offset:14336
	s_nop 1
	ds_read_b128 v[74:77], v246 offset:18432
	ds_read_b128 v[62:65], v246 offset:6144
	ds_read_b128 v[66:69], v246 offset:7168
	ds_read_b128 v[50:53], v246
	ds_read_b32 v175, v248 offset:20480
	v_cvt_pk_f16_f32 v103, v88, v89
	v_mfma_f32_16x16x32_f16 v[216:219], v[216:219], v[98:101], v[90:93]
	v_cvt_pk_f16_f32 v102, v86, v87
	v_pk_mul_f32 v[80:81], v[160:161], v[80:81] op_sel_hi:[0,1]
	v_pk_mul_f32 v[78:79], v[160:161], v[78:79] op_sel_hi:[0,1]
	ds_read_b128 v[90:93], v246 offset:19456
	v_mfma_f32_16x16x32_f16 v[176:179], v[176:179], v[102:105], v[220:223]
	v_mul_f32_e64 v96, v160, v96
	v_mul_f32_e64 v97, v160, v97
	v_pk_mul_f32 v[94:95], v[160:161], v[94:95] op_sel_hi:[0,1]
	v_pk_mul_f32 v[88:89], v[160:161], v[88:89] op_sel_hi:[0,1]
	v_mfma_f32_16x16x32_f16 v[146:149], v[146:149], v[102:105], v[224:227]
	v_mul_f32_e64 v86, v160, v86
	v_mul_f32_e64 v87, v160, v87
	v_pk_mul_f32 v[84:85], v[160:161], v[84:85] op_sel_hi:[0,1]
	v_pk_mul_f32 v[82:83], v[160:161], v[82:83] op_sel_hi:[0,1]
	v_mfma_f32_16x16x32_f16 v[142:145], v[142:145], v[102:105], v[228:231]
	v_lshl_add_u64 v[200:201], s[20:21], 0, v[158:159]
	s_nop 1
	v_cvt_pk_f16_f32 v149, v148, v149
	v_cvt_pk_f16_f32 v148, v146, v147
	v_mfma_f32_16x16x32_f16 v[134:137], v[134:137], v[102:105], v[216:219]
	v_cvt_pk_f16_f32 v147, v178, v179
	v_cvt_pk_f16_f32 v146, v176, v177
	s_mov_b32 s7, 0x1df0a000
	v_add_co_u32_e32 v176, vcc, s7, v200
	v_mfma_f32_16x16x32_f16 v[70:73], v[70:73], v[146:149], v[78:81]
	s_nop 2
	v_cvt_pk_f16_f32 v137, v136, v137
	v_cvt_pk_f16_f32 v136, v134, v135
	v_cvt_pk_f16_f32 v135, v144, v145
	v_mfma_f32_16x16x32_f16 v[38:41], v[38:41], v[146:149], v[94:97]
	v_cvt_pk_f16_f32 v134, v142, v143
	v_addc_co_u32_e32 v177, vcc, 0, v201, vcc
	v_mfma_f32_16x16x32_f16 v[30:33], v[30:33], v[146:149], v[86:89]
	s_mov_b32 s7, 0x1ef0a000
	s_add_i32 s6, s6, -1
	s_mov_b64 s[8:9], 0x4000
	v_mfma_f32_16x16x32_f16 v[42:45], v[42:45], v[146:149], v[82:85]
	global_store_dwordx4 v[176:177], v[98:101], off
	v_lshl_add_u64 v[156:157], v[156:157], 0, 4
	v_lshl_add_u64 v[158:159], v[158:159], 0, s[16:17]
	v_mfma_f32_16x16x32_f16 v[78:81], v[14:17], v[134:137], v[70:73]
	v_add_co_u32_e32 v14, vcc, s7, v200
	v_lshl_add_u64 v[150:151], v[150:151], 0, s[8:9]
	v_mfma_f32_16x16x32_f16 v[94:97], v[2:5], v[134:137], v[38:41]
	v_addc_co_u32_e32 v15, vcc, 0, v201, vcc
	global_store_dwordx4 v[176:177], v[102:105], off offset:1024
	global_store_dwordx4 v[14:15], v[146:149], off
	global_store_dwordx4 v[14:15], v[134:137], off offset:1024
	v_mfma_f32_16x16x32_f16 v[86:89], v[6:9], v[134:137], v[30:33]
	v_lshl_add_u64 v[152:153], v[152:153], 0, s[16:17]
	s_cmp_eq_u32 s6, 0
	s_waitcnt lgkmcnt(0)
	v_mov_b64_e32 v[14:15], v[106:107]
	v_mfma_f32_16x16x32_f16 v[82:85], v[10:13], v[134:137], v[42:45]
	v_mov_b64_e32 v[38:39], v[110:111]
	v_mov_b64_e32 v[2:3], v[114:115]
	v_mov_b64_e32 v[4:5], v[116:117]
	v_mov_b64_e32 v[40:41], v[112:113]
	v_mov_b64_e32 v[70:71], v[118:119]
	v_mov_b64_e32 v[30:31], v[122:123]
	v_mov_b64_e32 v[32:33], v[124:125]
	v_mov_b64_e32 v[16:17], v[108:109]
	v_mov_b64_e32 v[6:7], v[126:127]
	v_mov_b64_e32 v[10:11], v[130:131]
	v_mov_b64_e32 v[12:13], v[132:133]
	v_mov_b64_e32 v[42:43], v[138:139]
	v_mov_b64_e32 v[44:45], v[140:141]
	v_mov_b64_e32 v[8:9], v[128:129]
	v_mov_b64_e32 v[72:73], v[120:121]
	v_mov_b32_e32 v160, v175
	s_cbranch_scc0 .LBB0_956
; DI f4v mfma16(h8v a, h8v b, f4v c) { return __builtin_amdgcn_mfma_f32_16x16x32_f16(a, b, c, 0, 0, 0); }
; DI void dn_c2_unit(const Params& p, int dh, int w) {
;     ...
;     h8v Sb[2];
;     Sb[0] = pack8(S[0], S[1]); Sb[1] = pack8(S[2], S[3]);
;     h16* cs1 = cs + (size_t)n * 4096; h16* cv1 = cvn + (size_t)n * 4096;
;     *(h8v*)&cs1[((w * 2 + 0) * 64 + lane) * 8] = Sb[0];
;     *(h8v*)&cs1[((w * 2 + 1) * 64 + lane) * 8] = Sb[1];
;     f4v vn[4];
; #pragma unroll
;     for (int t = 0; t < 4; ++t) { vn[t] = uu[t]; vn[t] = mfma16(wA[t][0], Sb[0], vn[t]); vn[t] = mfma16(wA[t][1], Sb[1], vn[t]); }
;     h8v Vb[2];
;     Vb[0] = pack8(vn[0], vn[1]); Vb[1] = pack8(vn[2], vn[3]);
;     *(h8v*)&cv1[((w * 2 + 0) * 64 + lane) * 8] = Vb[0];
;     *(h8v*)&cv1[((w * 2 + 1) * 64 + lane) * 8] = Vb[1];
; #pragma unroll
;     for (int t = 0; t < 4; ++t) { S[t] *= dl; S[t] = mfma16(kA[t][0], Vb[0], S[t]); S[t] = mfma16(kA[t][1], Vb[1], S[t]); }
	v_cvt_pk_f16_f32 v5, v96, v97
	v_cvt_pk_f16_f32 v4, v94, v95
	v_cvt_pk_f16_f32 v3, v80, v81
	v_cvt_pk_f16_f32 v2, v78, v79
	v_cvt_pk_f16_f32 v9, v84, v85
	v_cvt_pk_f16_f32 v8, v82, v83
	v_mfma_f32_16x16x32_f16 v[10:13], v[50:53], v[2:5], v[58:61]
	v_cvt_pk_f16_f32 v7, v88, v89
	v_cvt_pk_f16_f32 v6, v86, v87
	v_readlane_b32 s6, v254, 36
	v_mfma_f32_16x16x32_f16 v[14:17], v[26:29], v[2:5], v[54:57]
	v_readlane_b32 s7, v254, 37
	v_mfma_f32_16x16x32_f16 v[10:13], v[18:21], v[6:9], v[10:13]
	v_lshlrev_b64 v[18:19], 1, v[154:155]
	v_lshl_add_u64 v[20:21], s[6:7], 0, v[18:19]
	v_readlane_b32 s6, v254, 38
	v_readlane_b32 s7, v254, 39
	v_mfma_f32_16x16x32_f16 v[14:17], v[22:25], v[6:9], v[14:17]
	v_mov_b32_e32 v23, v0
	v_lshl_add_u64 v[26:27], s[6:7], 0, v[18:19]
	v_or_b32_e32 v18, v174, v171
	s_mov_b64 s[6:7], 0x1fe000
	v_lshlrev_b32_e32 v22, 1, v18
	v_lshl_add_u64 v[24:25], v[20:21], 0, s[6:7]
	v_lshl_add_u64 v[28:29], v[24:25], 0, v[22:23]
	v_mfma_f32_16x16x32_f16 v[18:21], v[34:37], v[2:5], v[74:77]
	global_store_dwordx4 v[28:29], v[2:5], off
	v_or_b32_e32 v28, 0x400, v22
	v_mov_b32_e32 v29, v0
	s_waitcnt vmcnt(5)
	v_mfma_f32_16x16x32_f16 v[2:5], v[62:65], v[2:5], v[90:93]
	v_lshl_add_u64 v[24:25], v[24:25], 0, v[28:29]
	global_store_dwordx4 v[24:25], v[6:9], off
	v_lshl_add_u64 v[24:25], v[26:27], 0, s[6:7]
	v_mfma_f32_16x16x32_f16 v[18:21], v[46:49], v[6:9], v[18:21]
	v_cvt_pk_f16_f32 v17, v16, v17
	v_cvt_pk_f16_f32 v16, v14, v15
	v_cvt_pk_f16_f32 v15, v12, v13
	v_mfma_f32_16x16x32_f16 v[2:5], v[66:69], v[6:9], v[2:5]
	v_cvt_pk_f16_f32 v14, v10, v11
	v_lshl_add_u64 v[6:7], v[24:25], 0, v[22:23]
	global_store_dwordx4 v[6:7], v[14:17], off
	v_lshl_add_u64 v[6:7], v[24:25], 0, v[28:29]
	s_nop 3
	v_cvt_pk_f16_f32 v5, v4, v5
	v_cvt_pk_f16_f32 v4, v2, v3
	v_cvt_pk_f16_f32 v3, v20, v21
	v_cvt_pk_f16_f32 v2, v18, v19
	global_store_dwordx4 v[6:7], v[2:5], off
	s_waitcnt vmcnt(0)
